# combo22: combo21 with the 16 V-fragment LDS reads of the diff-attention off-diagonal tiles issued in the MFMA-to-exp wait slot (replacing s_nop 11) instead of at the tile top; K reads waited progressi
# speedup vs baseline: 1.0034x; 1.0034x over previous
; template <int TYPE> __device__ __forceinline__ void attn_unit(const AttnCtx& C, int b, int h, int qb, LAS unsigned char* lds, int tid_in, unsigned* counter) {
;     ...
;             if (active) {
;                 f32x16 p0, p1;
;                 const LAS unsigned char* kp = Kb + bo + hi * 1024 + r32 * 16;
; #pragma unroll
;                 for (int d0 = 0; d0 < 4; ++d0) {
;                     const bf16x8 a0 = *(const LAS bf16x8*)(kp + d0 * 2048), a1 = *(const LAS bf16x8*)(kp + d0 * 2048 + 512);
;                     if (d0 == 0) { p0 = MFMA32(a0, qr[0], (TYPE == 1 ? cvec : zvec)); p1 = MFMA32(a1, qr[0], (TYPE == 1 ? cvec : zvec)); }
;                     else { p0 = MFMA32(a0, qr[d0], p0); p1 = MFMA32(a1, qr[d0], p1); }
;                 }
;                 const int xi = sq - 64 * t - 4 * hi;
;                 if (TYPE == 0) {
;                     const float xf = (float)xi;
; #pragma unroll
;                     for (int r = 0; r < 16; ++r) { const float c = (float)((r & 3) + 8 * (r >> 2));
;                         p0[r] = fast_exp2(p0[r] - sl2 * fabsf(xf - c)); p1[r] = fast_exp2(p1[r] - sl2 * fabsf(xf - (c + 32.f))); }
;                 } else if (TYPE == 1) {
;                     const LAS float* fp = Fb + (t & 3) * 64 + 4 * hi;
; #pragma unroll
;                     for (int g = 0; g < 4; ++g) { const f32x4 fa = *(const LAS f32x4*)(fp + 8 * g), fb2 = *(const LAS f32x4*)(fp + 32 + 8 * g);
; #pragma unroll
;                         for (int i = 0; i < 4; i += 2) {
;                             const f32x2_t d0_ = (f32x2_t){p0[4 * g + i], p0[4 * g + i + 1]} - (f32x2_t){fa[i], fa[i + 1]}, d1_ = (f32x2_t){p1[4 * g + i], p1[4 * g + i + 1]} - (f32x2_t){fb2[i], fb2[i + 1]};
;                             p0[4 * g + i] = fast_exp2(d0_[0]); p0[4 * g + i + 1] = fast_exp2(d0_[1]); p1[4 * g + i] = fast_exp2(d1_[0]); p1[4 * g + i + 1] = fast_exp2(d1_[1]); } }
;                     if (t == cq) { const int qrel = 32 * (w & 1) + r32;
; #pragma unroll
;                         for (int r = 0; r < 16; ++r) { const int kv = crow(r, hi); if (kv > qrel) p0[r] = 0.f; if (kv + 32 > qrel) p1[r] = 0.f; } }
;                 } else {
;                     if (cq - t >= 3) { const float bc = relb[256];
; #pragma unroll
;                         for (int r = 0; r < 16; ++r) { p0[r] = fast_exp2(p0[r] + bc); p1[r] = fast_exp2(p1[r] + bc); }
;                     } else {
.LBB0_438:
	s_cmp_gt_i32 s4, s14
	s_cbranch_scc1 .LBB0_433
	s_sub_i32 s6, s1, 63
	v_cvt_f32_i32_e32 v32, s6
	v_cmp_ngt_f32_e32 vcc, v168, v32
	s_cbranch_vccnz .LBB0_433
	s_cmp_eq_u32 s4, s14
	s_cbranch_scc1 .Lt0diag_4
	v_add_u32_e32 v118, s5, v171
	v_add_u32_e32 v213, s1, v172
	v_cvt_f32_i32_e32 v213, v213
	v_mul_f32_e64 v210, -v167, v213
	ds_read_b128 v[202:205], v118
	ds_read_b128 v[206:209], v118 offset:512
	ds_read_b128 v[110:113], v118 offset:2048
	ds_read_b128 v[114:117], v118 offset:2560
	ds_read_b128 v[122:125], v118 offset:4608
	ds_read_b128 v[126:129], v118 offset:6144
	ds_read_b128 v[130:133], v118 offset:6656
	ds_read_b128 v[118:121], v118 offset:4096
	v_add_u32_e32 v134, s5, v170
	v_mov_b32_e32 v48, v210
	v_fmamk_f32 v49, v167, 0x3f800000, v210
	v_fmamk_f32 v50, v167, 0x40000000, v210
	v_fmamk_f32 v51, v167, 0x40400000, v210
	v_fmamk_f32 v52, v167, 0x41000000, v210
	v_fmamk_f32 v53, v167, 0x41100000, v210
	v_fmamk_f32 v54, v167, 0x41200000, v210
	v_fmamk_f32 v55, v167, 0x41300000, v210
	v_fmamk_f32 v56, v167, 0x41800000, v210
	v_fmamk_f32 v57, v167, 0x41880000, v210
	v_fmamk_f32 v58, v167, 0x41900000, v210
	v_fmamk_f32 v59, v167, 0x41980000, v210
	v_fmamk_f32 v60, v167, 0x41c00000, v210
	v_fmamk_f32 v61, v167, 0x41c80000, v210
	v_fmamk_f32 v62, v167, 0x41d00000, v210
	v_fmamk_f32 v63, v167, 0x41d80000, v210
	v_fmamk_f32 v32, v167, 0x42000000, v210
	v_fmamk_f32 v33, v167, 0x42040000, v210
	v_fmamk_f32 v34, v167, 0x42080000, v210
	v_fmamk_f32 v35, v167, 0x420c0000, v210
	v_fmamk_f32 v36, v167, 0x42200000, v210
	v_fmamk_f32 v37, v167, 0x42240000, v210
	v_fmamk_f32 v38, v167, 0x42280000, v210
	v_fmamk_f32 v39, v167, 0x422c0000, v210
	v_fmamk_f32 v40, v167, 0x42400000, v210
	v_fmamk_f32 v41, v167, 0x42440000, v210
	v_fmamk_f32 v42, v167, 0x42480000, v210
	v_fmamk_f32 v43, v167, 0x424c0000, v210
	v_fmamk_f32 v44, v167, 0x42600000, v210
	v_fmamk_f32 v45, v167, 0x42640000, v210
	v_fmamk_f32 v46, v167, 0x42680000, v210
	v_fmamk_f32 v47, v167, 0x426c0000, v210
	s_waitcnt vmcnt(7) lgkmcnt(6)
	v_mfma_f32_32x32x16_bf16 v[48:63], v[202:205], v[64:67], v[48:63]
	v_mfma_f32_32x32x16_bf16 v[32:47], v[206:209], v[64:67], v[32:47]
	s_waitcnt vmcnt(6) lgkmcnt(4)
	v_mfma_f32_32x32x16_bf16 v[32:47], v[114:117], v[68:71], v[32:47]
	v_mfma_f32_32x32x16_bf16 v[48:63], v[110:113], v[68:71], v[48:63]
	s_waitcnt vmcnt(5) lgkmcnt(0)
	v_mfma_f32_32x32x16_bf16 v[32:47], v[122:125], v[72:75], v[32:47]
	v_mfma_f32_32x32x16_bf16 v[48:63], v[118:121], v[72:75], v[48:63]
	s_waitcnt vmcnt(4)
	v_mfma_f32_32x32x16_bf16 v[32:47], v[130:133], v[76:79], v[32:47]
	v_mfma_f32_32x32x16_bf16 v[48:63], v[126:129], v[76:79], v[48:63]
	ds_read_b64_tr_b16 v[214:215], v134 offset:32768
	ds_read_b64_tr_b16 v[216:217], v134 offset:33280
	ds_read_b64_tr_b16 v[218:219], v134 offset:33792
	ds_read_b64_tr_b16 v[220:221], v134 offset:34304
	ds_read_b64_tr_b16 v[222:223], v134 offset:34816
	ds_read_b64_tr_b16 v[224:225], v134 offset:35328
	ds_read_b64_tr_b16 v[226:227], v134 offset:35840
	ds_read_b64_tr_b16 v[228:229], v134 offset:36352
	ds_read_b64_tr_b16 v[230:231], v134 offset:36864
	ds_read_b64_tr_b16 v[232:233], v134 offset:37376
	ds_read_b64_tr_b16 v[234:235], v134 offset:37888
	ds_read_b64_tr_b16 v[236:237], v134 offset:38400
	ds_read_b64_tr_b16 v[238:239], v134 offset:38912
	ds_read_b64_tr_b16 v[240:241], v134 offset:39424
	ds_read_b64_tr_b16 v[242:243], v134 offset:39936
	ds_read_b64_tr_b16 v[244:245], v134 offset:40448
	v_exp_f32_e32 v32, v32
	v_exp_f32_e32 v110, v52
	v_exp_f32_e32 v112, v36
	v_exp_f32_e32 v111, v53
	v_exp_f32_e32 v113, v37
	v_exp_f32_e32 v114, v54
	v_exp_f32_e32 v116, v38
	v_exp_f32_e32 v115, v55
	v_exp_f32_e32 v117, v39
	v_exp_f32_e32 v118, v56
	v_exp_f32_e32 v120, v40
	v_exp_f32_e32 v119, v57
	v_exp_f32_e32 v121, v41
	v_exp_f32_e32 v122, v58
	v_exp_f32_e32 v124, v42
	v_exp_f32_e32 v123, v59
	v_exp_f32_e32 v125, v43
	v_exp_f32_e32 v126, v60
	v_exp_f32_e32 v128, v44
	v_exp_f32_e32 v127, v61
	v_exp_f32_e32 v129, v45
	v_exp_f32_e32 v48, v48
	v_exp_f32_e32 v49, v49
	v_exp_f32_e32 v50, v50
	v_exp_f32_e32 v51, v51
	v_exp_f32_e32 v130, v62
	v_exp_f32_e32 v132, v46
	v_exp_f32_e32 v131, v63
	v_cvt_pk_bf16_f32 v36, v48, v49
	v_cvt_pk_bf16_f32 v37, v50, v51
	v_cvt_pk_bf16_f32 v38, v110, v111
	v_cvt_pk_bf16_f32 v39, v114, v115
	s_waitcnt lgkmcnt(0)
	s_nop 0
	v_mfma_f32_32x32x16_bf16 v[16:31], v[36:39], v[214:217], v[16:31]
	v_cvt_pk_bf16_f32 v52, v118, v119
	v_cvt_pk_bf16_f32 v53, v122, v123
	v_cvt_pk_bf16_f32 v54, v126, v127
	v_cvt_pk_bf16_f32 v55, v130, v131
	v_exp_f32_e32 v33, v33
	v_exp_f32_e32 v34, v34
	v_exp_f32_e32 v35, v35
	s_waitcnt lgkmcnt(0)
	v_mfma_f32_32x32x16_bf16 v[16:31], v[52:55], v[218:221], v[16:31]
	v_exp_f32_e32 v133, v47
	v_cvt_pk_bf16_f32 v40, v32, v33
	v_cvt_pk_bf16_f32 v41, v34, v35
	v_cvt_pk_bf16_f32 v42, v112, v113
	v_cvt_pk_bf16_f32 v43, v116, v117
	s_waitcnt lgkmcnt(0)
	s_nop 0
	v_mfma_f32_32x32x16_bf16 v[16:31], v[40:43], v[222:225], v[16:31]
	v_cvt_pk_bf16_f32 v56, v120, v121
	v_cvt_pk_bf16_f32 v57, v124, v125
	v_cvt_pk_bf16_f32 v58, v128, v129
	v_cvt_pk_bf16_f32 v59, v132, v133
	s_waitcnt lgkmcnt(0)
	s_nop 0
	v_mfma_f32_32x32x16_bf16 v[16:31], v[56:59], v[226:229], v[16:31]
	s_waitcnt lgkmcnt(2)
	v_mfma_f32_32x32x16_bf16 v[0:15], v[36:39], v[230:233], v[0:15]
	v_add_f32_e64 v36, v48, 0
	v_add_f32_e64 v37, v49, 0
	v_add_f32_e64 v32, v32, v36
	v_add_f32_e64 v33, v33, v37
	v_add_f32_e64 v32, v50, v32
	v_add_f32_e64 v33, v51, v33
	v_pk_add_f32 v[32:33], v[34:35], v[32:33]
	s_waitcnt lgkmcnt(0)
	v_mfma_f32_32x32x16_bf16 v[0:15], v[52:55], v[234:237], v[0:15]
	v_add_f32_e64 v32, v110, v32
	v_add_f32_e64 v33, v111, v33
	v_add_f32_e64 v32, v112, v32
	v_add_f32_e64 v33, v113, v33
	v_add_f32_e64 v32, v114, v32
	v_add_f32_e64 v33, v115, v33
	v_pk_add_f32 v[36:37], v[116:117], v[32:33]
	s_waitcnt lgkmcnt(0)
	v_mfma_f32_32x32x16_bf16 v[0:15], v[40:43], v[238:241], v[0:15]
	v_add_f32_e64 v36, v118, v36
	v_add_f32_e64 v37, v119, v37
	v_add_f32_e64 v44, v120, v36
	v_add_f32_e64 v45, v121, v37
	v_pk_add_f32 v[32:33], v[122:123], v[44:45]
	s_nop 0
	v_pk_add_f32 v[32:33], v[124:125], v[32:33]
	s_waitcnt lgkmcnt(0)
	v_mfma_f32_32x32x16_bf16 v[0:15], v[56:59], v[242:245], v[0:15]
	v_add_f32_e64 v32, v126, v32
	v_add_f32_e64 v33, v127, v33
	v_add_f32_e64 v32, v128, v32
	v_add_f32_e64 v33, v129, v33
	v_add_f32_e64 v32, v130, v32
	v_add_f32_e64 v33, v131, v33
	v_pk_add_f32 v[32:33], v[132:133], v[32:33]
	s_nop 0
	v_add_f32_e32 v32, v32, v33
	v_add_f32_e32 v109, v109, v32
	s_branch .LBB0_433

; template <int TYPE> __device__ __forceinline__ void attn_unit(const AttnCtx& C, int b, int h, int qb, LAS unsigned char* lds, int tid_in, unsigned* counter) {
;     ...
;             if (active) {
;                 f32x16 p0, p1;
;                 const LAS unsigned char* kp = Kb + bo + hi * 1024 + r32 * 16;
; #pragma unroll
;                 for (int d0 = 0; d0 < 4; ++d0) {
;                     const bf16x8 a0 = *(const LAS bf16x8*)(kp + d0 * 2048), a1 = *(const LAS bf16x8*)(kp + d0 * 2048 + 512);
;                     if (d0 == 0) { p0 = MFMA32(a0, qr[0], (TYPE == 1 ? cvec : zvec)); p1 = MFMA32(a1, qr[0], (TYPE == 1 ? cvec : zvec)); }
;                     else { p0 = MFMA32(a0, qr[d0], p0); p1 = MFMA32(a1, qr[d0], p1); }
;                 }
;                 const int xi = sq - 64 * t - 4 * hi;
;                 if (TYPE == 0) {
;                     const float xf = (float)xi;
; #pragma unroll
;                     for (int r = 0; r < 16; ++r) { const float c = (float)((r & 3) + 8 * (r >> 2));
;                         p0[r] = fast_exp2(p0[r] - sl2 * fabsf(xf - c)); p1[r] = fast_exp2(p1[r] - sl2 * fabsf(xf - (c + 32.f))); }
;                 } else if (TYPE == 1) {
;                     const LAS float* fp = Fb + (t & 3) * 64 + 4 * hi;
; #pragma unroll
;                     for (int g = 0; g < 4; ++g) { const f32x4 fa = *(const LAS f32x4*)(fp + 8 * g), fb2 = *(const LAS f32x4*)(fp + 32 + 8 * g);
; #pragma unroll
;                         for (int i = 0; i < 4; i += 2) {
;                             const f32x2_t d0_ = (f32x2_t){p0[4 * g + i], p0[4 * g + i + 1]} - (f32x2_t){fa[i], fa[i + 1]}, d1_ = (f32x2_t){p1[4 * g + i], p1[4 * g + i + 1]} - (f32x2_t){fb2[i], fb2[i + 1]};
;                             p0[4 * g + i] = fast_exp2(d0_[0]); p0[4 * g + i + 1] = fast_exp2(d0_[1]); p1[4 * g + i] = fast_exp2(d1_[0]); p1[4 * g + i + 1] = fast_exp2(d1_[1]); } }
;                     if (t == cq) { const int qrel = 32 * (w & 1) + r32;
; #pragma unroll
;                         for (int r = 0; r < 16; ++r) { const int kv = crow(r, hi); if (kv > qrel) p0[r] = 0.f; if (kv + 32 > qrel) p1[r] = 0.f; } }
;                 } else {
;                     if (cq - t >= 3) { const float bc = relb[256];
; #pragma unroll
;                         for (int r = 0; r < 16; ++r) { p0[r] = fast_exp2(p0[r] + bc); p1[r] = fast_exp2(p1[r] + bc); }
;                     } else {
.LBB0_454:
	s_cmp_gt_i32 s15, s14
	s_cbranch_scc1 .LBB0_445
	s_sub_i32 s0, s6, 63
	s_waitcnt vmcnt(15)
	v_cvt_f32_i32_e32 v64, s0
	v_cmp_ngt_f32_e32 vcc, v168, v64
	s_cbranch_vccnz .LBB0_445
	s_cmp_eq_u32 s15, s14
	s_cbranch_scc1 .Lt0diag_3
	v_add_u32_e32 v184, s16, v171
	v_add_u32_e32 v213, s6, v172
	v_cvt_f32_i32_e32 v213, v213
	v_mul_f32_e64 v210, -v167, v213
	ds_read_b128 v[202:205], v184
	ds_read_b128 v[206:209], v184 offset:512
	ds_read_b128 v[176:179], v184 offset:2048
	ds_read_b128 v[180:183], v184 offset:2560
	ds_read_b128 v[188:191], v184 offset:4608
	ds_read_b128 v[192:195], v184 offset:6144
	ds_read_b128 v[196:199], v184 offset:6656
	ds_read_b128 v[184:187], v184 offset:4096
	s_waitcnt vmcnt(14)
	v_add_u32_e32 v200, s16, v170
	v_mov_b32_e32 v80, v210
	v_fmamk_f32 v81, v167, 0x3f800000, v210
	v_fmamk_f32 v82, v167, 0x40000000, v210
	v_fmamk_f32 v83, v167, 0x40400000, v210
	v_fmamk_f32 v84, v167, 0x41000000, v210
	v_fmamk_f32 v85, v167, 0x41100000, v210
	v_fmamk_f32 v86, v167, 0x41200000, v210
	v_fmamk_f32 v87, v167, 0x41300000, v210
	v_fmamk_f32 v88, v167, 0x41800000, v210
	v_fmamk_f32 v89, v167, 0x41880000, v210
	v_fmamk_f32 v90, v167, 0x41900000, v210
	v_fmamk_f32 v91, v167, 0x41980000, v210
	v_fmamk_f32 v92, v167, 0x41c00000, v210
	v_fmamk_f32 v93, v167, 0x41c80000, v210
	v_fmamk_f32 v94, v167, 0x41d00000, v210
	v_fmamk_f32 v95, v167, 0x41d80000, v210
	v_fmamk_f32 v64, v167, 0x42000000, v210
	v_fmamk_f32 v65, v167, 0x42040000, v210
	v_fmamk_f32 v66, v167, 0x42080000, v210
	v_fmamk_f32 v67, v167, 0x420c0000, v210
	v_fmamk_f32 v68, v167, 0x42200000, v210
	v_fmamk_f32 v69, v167, 0x42240000, v210
	v_fmamk_f32 v70, v167, 0x42280000, v210
	v_fmamk_f32 v71, v167, 0x422c0000, v210
	v_fmamk_f32 v72, v167, 0x42400000, v210
	v_fmamk_f32 v73, v167, 0x42440000, v210
	v_fmamk_f32 v74, v167, 0x42480000, v210
	v_fmamk_f32 v75, v167, 0x424c0000, v210
	v_fmamk_f32 v76, v167, 0x42600000, v210
	v_fmamk_f32 v77, v167, 0x42640000, v210
	v_fmamk_f32 v78, v167, 0x42680000, v210
	v_fmamk_f32 v79, v167, 0x426c0000, v210
	s_waitcnt vmcnt(7) lgkmcnt(6)
	v_mfma_f32_32x32x16_bf16 v[80:95], v[202:205], v[112:115], v[80:95]
	v_mfma_f32_32x32x16_bf16 v[64:79], v[206:209], v[112:115], v[64:79]
	s_waitcnt vmcnt(6) lgkmcnt(4)
	v_mfma_f32_32x32x16_bf16 v[64:79], v[180:183], v[116:119], v[64:79]
	v_mfma_f32_32x32x16_bf16 v[80:95], v[176:179], v[116:119], v[80:95]
	s_waitcnt vmcnt(5) lgkmcnt(0)
	v_mfma_f32_32x32x16_bf16 v[64:79], v[188:191], v[120:123], v[64:79]
	v_mfma_f32_32x32x16_bf16 v[80:95], v[184:187], v[120:123], v[80:95]
	s_waitcnt vmcnt(4)
	v_mfma_f32_32x32x16_bf16 v[64:79], v[196:199], v[124:127], v[64:79]
	v_mfma_f32_32x32x16_bf16 v[80:95], v[192:195], v[124:127], v[80:95]
	ds_read_b64_tr_b16 v[214:215], v200 offset:32768
	ds_read_b64_tr_b16 v[216:217], v200 offset:33280
	ds_read_b64_tr_b16 v[218:219], v200 offset:33792
	ds_read_b64_tr_b16 v[220:221], v200 offset:34304
	ds_read_b64_tr_b16 v[222:223], v200 offset:34816
	ds_read_b64_tr_b16 v[224:225], v200 offset:35328
	ds_read_b64_tr_b16 v[226:227], v200 offset:35840
	ds_read_b64_tr_b16 v[228:229], v200 offset:36352
	ds_read_b64_tr_b16 v[230:231], v200 offset:36864
	ds_read_b64_tr_b16 v[232:233], v200 offset:37376
	ds_read_b64_tr_b16 v[234:235], v200 offset:37888
	ds_read_b64_tr_b16 v[236:237], v200 offset:38400
	ds_read_b64_tr_b16 v[238:239], v200 offset:38912
	ds_read_b64_tr_b16 v[240:241], v200 offset:39424
	ds_read_b64_tr_b16 v[242:243], v200 offset:39936
	ds_read_b64_tr_b16 v[244:245], v200 offset:40448
	v_exp_f32_e32 v64, v64
	v_exp_f32_e32 v176, v84
	v_exp_f32_e32 v178, v68
	v_exp_f32_e32 v177, v85
	v_exp_f32_e32 v179, v69
	v_exp_f32_e32 v180, v86
	v_exp_f32_e32 v182, v70
	v_exp_f32_e32 v181, v87
	v_exp_f32_e32 v183, v71
	v_exp_f32_e32 v184, v88
	v_exp_f32_e32 v186, v72
	v_exp_f32_e32 v185, v89
	v_exp_f32_e32 v187, v73
	v_exp_f32_e32 v188, v90
	v_exp_f32_e32 v190, v74
	v_exp_f32_e32 v189, v91
	v_exp_f32_e32 v191, v75
	v_exp_f32_e32 v192, v92
	v_exp_f32_e32 v194, v76
	v_exp_f32_e32 v193, v93
	v_exp_f32_e32 v195, v77
	v_exp_f32_e32 v80, v80
	v_exp_f32_e32 v81, v81
	v_exp_f32_e32 v82, v82
	v_exp_f32_e32 v83, v83
	v_exp_f32_e32 v196, v94
	v_exp_f32_e32 v198, v78
	v_exp_f32_e32 v197, v95
	v_cvt_pk_bf16_f32 v68, v80, v81
	v_cvt_pk_bf16_f32 v69, v82, v83
	v_cvt_pk_bf16_f32 v70, v176, v177
	v_cvt_pk_bf16_f32 v71, v180, v181
	s_waitcnt lgkmcnt(0)
	s_nop 0
	v_mfma_f32_32x32x16_bf16 v[48:63], v[68:71], v[214:217], v[48:63]
	v_cvt_pk_bf16_f32 v84, v184, v185
	v_cvt_pk_bf16_f32 v85, v188, v189
	v_cvt_pk_bf16_f32 v86, v192, v193
	v_cvt_pk_bf16_f32 v87, v196, v197
	v_exp_f32_e32 v65, v65
	v_exp_f32_e32 v66, v66
	v_exp_f32_e32 v67, v67
	s_waitcnt lgkmcnt(0)
	v_mfma_f32_32x32x16_bf16 v[48:63], v[84:87], v[218:221], v[48:63]
	v_exp_f32_e32 v199, v79
	v_cvt_pk_bf16_f32 v72, v64, v65
	v_cvt_pk_bf16_f32 v73, v66, v67
	v_cvt_pk_bf16_f32 v74, v178, v179
	v_cvt_pk_bf16_f32 v75, v182, v183
	s_waitcnt lgkmcnt(0)
	s_nop 0
	v_mfma_f32_32x32x16_bf16 v[48:63], v[72:75], v[222:225], v[48:63]
	v_cvt_pk_bf16_f32 v88, v186, v187
	v_cvt_pk_bf16_f32 v89, v190, v191
	v_cvt_pk_bf16_f32 v90, v194, v195
	v_cvt_pk_bf16_f32 v91, v198, v199
	s_waitcnt lgkmcnt(0)
	s_nop 0
	v_mfma_f32_32x32x16_bf16 v[48:63], v[88:91], v[226:229], v[48:63]
	s_waitcnt lgkmcnt(2)
	v_mfma_f32_32x32x16_bf16 v[32:47], v[68:71], v[230:233], v[32:47]
	v_add_f32_e64 v68, v80, 0
	v_add_f32_e64 v69, v81, 0
	v_add_f32_e64 v64, v64, v68
	v_add_f32_e64 v65, v65, v69
	v_add_f32_e64 v64, v82, v64
	v_add_f32_e64 v65, v83, v65
	v_pk_add_f32 v[64:65], v[66:67], v[64:65]
	s_waitcnt lgkmcnt(0)
	v_mfma_f32_32x32x16_bf16 v[32:47], v[84:87], v[234:237], v[32:47]
	v_add_f32_e64 v64, v176, v64
	v_add_f32_e64 v65, v177, v65
	v_add_f32_e64 v64, v178, v64
	v_add_f32_e64 v65, v179, v65
	v_add_f32_e64 v64, v180, v64
	v_add_f32_e64 v65, v181, v65
	v_pk_add_f32 v[68:69], v[182:183], v[64:65]
	s_waitcnt lgkmcnt(0)
	v_mfma_f32_32x32x16_bf16 v[32:47], v[72:75], v[238:241], v[32:47]
	v_add_f32_e64 v68, v184, v68
	v_add_f32_e64 v69, v185, v69
	v_add_f32_e64 v76, v186, v68
	v_add_f32_e64 v77, v187, v69
	v_pk_add_f32 v[64:65], v[188:189], v[76:77]
	s_nop 0
	v_pk_add_f32 v[64:65], v[190:191], v[64:65]
	s_waitcnt lgkmcnt(0)
	v_mfma_f32_32x32x16_bf16 v[32:47], v[88:91], v[242:245], v[32:47]
	v_add_f32_e64 v64, v192, v64
	v_add_f32_e64 v65, v193, v65
	v_add_f32_e64 v64, v194, v64
	v_add_f32_e64 v65, v195, v65
	v_add_f32_e64 v64, v196, v64
	v_add_f32_e64 v65, v197, v65
	v_pk_add_f32 v[64:65], v[198:199], v[64:65]
	s_nop 0
	v_add_f32_e32 v64, v64, v65
	v_add_f32_e32 v175, v175, v64
	s_branch .LBB0_445

; template <int TYPE> __device__ __forceinline__ void attn_unit(const AttnCtx& C, int b, int h, int qb, LAS unsigned char* lds, int tid_in, unsigned* counter) {
;     ...
;             if (active) {
;                 f32x16 p0, p1;
;                 const LAS unsigned char* kp = Kb + bo + hi * 1024 + r32 * 16;
; #pragma unroll
;                 for (int d0 = 0; d0 < 4; ++d0) {
;                     const bf16x8 a0 = *(const LAS bf16x8*)(kp + d0 * 2048), a1 = *(const LAS bf16x8*)(kp + d0 * 2048 + 512);
;                     if (d0 == 0) { p0 = MFMA32(a0, qr[0], (TYPE == 1 ? cvec : zvec)); p1 = MFMA32(a1, qr[0], (TYPE == 1 ? cvec : zvec)); }
;                     else { p0 = MFMA32(a0, qr[d0], p0); p1 = MFMA32(a1, qr[d0], p1); }
;                 }
;                 const int xi = sq - 64 * t - 4 * hi;
;                 if (TYPE == 0) {
;                     const float xf = (float)xi;
; #pragma unroll
;                     for (int r = 0; r < 16; ++r) { const float c = (float)((r & 3) + 8 * (r >> 2));
;                         p0[r] = fast_exp2(p0[r] - sl2 * fabsf(xf - c)); p1[r] = fast_exp2(p1[r] - sl2 * fabsf(xf - (c + 32.f))); }
;                 } else if (TYPE == 1) {
;                     const LAS float* fp = Fb + (t & 3) * 64 + 4 * hi;
; #pragma unroll
;                     for (int g = 0; g < 4; ++g) { const f32x4 fa = *(const LAS f32x4*)(fp + 8 * g), fb2 = *(const LAS f32x4*)(fp + 32 + 8 * g);
; #pragma unroll
;                         for (int i = 0; i < 4; i += 2) {
;                             const f32x2_t d0_ = (f32x2_t){p0[4 * g + i], p0[4 * g + i + 1]} - (f32x2_t){fa[i], fa[i + 1]}, d1_ = (f32x2_t){p1[4 * g + i], p1[4 * g + i + 1]} - (f32x2_t){fb2[i], fb2[i + 1]};
;                             p0[4 * g + i] = fast_exp2(d0_[0]); p0[4 * g + i + 1] = fast_exp2(d0_[1]); p1[4 * g + i] = fast_exp2(d1_[0]); p1[4 * g + i + 1] = fast_exp2(d1_[1]); } }
;                     if (t == cq) { const int qrel = 32 * (w & 1) + r32;
; #pragma unroll
;                         for (int r = 0; r < 16; ++r) { const int kv = crow(r, hi); if (kv > qrel) p0[r] = 0.f; if (kv + 32 > qrel) p1[r] = 0.f; } }
;                 } else {
;                     if (cq - t >= 3) { const float bc = relb[256];
; #pragma unroll
;                         for (int r = 0; r < 16; ++r) { p0[r] = fast_exp2(p0[r] + bc); p1[r] = fast_exp2(p1[r] + bc); }
;                     } else {
.LBB0_1364:
	s_cmp_gt_i32 s3, s12
	s_cbranch_scc1 .LBB0_1359
	s_sub_i32 s7, s0, 63
	v_cvt_f32_i32_e32 v32, s7
	v_cmp_ngt_f32_e32 vcc, v168, v32
	s_cbranch_vccnz .LBB0_1359
	s_cmp_eq_u32 s3, s12
	s_cbranch_scc1 .Lt0diag_2
	v_add_u32_e32 v118, s6, v171
	v_add_u32_e32 v213, s0, v172
	v_cvt_f32_i32_e32 v213, v213
	v_mul_f32_e64 v210, -v167, v213
	ds_read_b128 v[202:205], v118
	ds_read_b128 v[206:209], v118 offset:512
	ds_read_b128 v[110:113], v118 offset:2048
	ds_read_b128 v[114:117], v118 offset:2560
	ds_read_b128 v[122:125], v118 offset:4608
	ds_read_b128 v[126:129], v118 offset:6144
	ds_read_b128 v[130:133], v118 offset:6656
	ds_read_b128 v[118:121], v118 offset:4096
	v_add_u32_e32 v134, s6, v170
	v_mov_b32_e32 v48, v210
	v_fmamk_f32 v49, v167, 0x3f800000, v210
	v_fmamk_f32 v50, v167, 0x40000000, v210
	v_fmamk_f32 v51, v167, 0x40400000, v210
	v_fmamk_f32 v52, v167, 0x41000000, v210
	v_fmamk_f32 v53, v167, 0x41100000, v210
	v_fmamk_f32 v54, v167, 0x41200000, v210
	v_fmamk_f32 v55, v167, 0x41300000, v210
	v_fmamk_f32 v56, v167, 0x41800000, v210
	v_fmamk_f32 v57, v167, 0x41880000, v210
	v_fmamk_f32 v58, v167, 0x41900000, v210
	v_fmamk_f32 v59, v167, 0x41980000, v210
	v_fmamk_f32 v60, v167, 0x41c00000, v210
	v_fmamk_f32 v61, v167, 0x41c80000, v210
	v_fmamk_f32 v62, v167, 0x41d00000, v210
	v_fmamk_f32 v63, v167, 0x41d80000, v210
	v_fmamk_f32 v32, v167, 0x42000000, v210
	v_fmamk_f32 v33, v167, 0x42040000, v210
	v_fmamk_f32 v34, v167, 0x42080000, v210
	v_fmamk_f32 v35, v167, 0x420c0000, v210
	v_fmamk_f32 v36, v167, 0x42200000, v210
	v_fmamk_f32 v37, v167, 0x42240000, v210
	v_fmamk_f32 v38, v167, 0x42280000, v210
	v_fmamk_f32 v39, v167, 0x422c0000, v210
	v_fmamk_f32 v40, v167, 0x42400000, v210
	v_fmamk_f32 v41, v167, 0x42440000, v210
	v_fmamk_f32 v42, v167, 0x42480000, v210
	v_fmamk_f32 v43, v167, 0x424c0000, v210
	v_fmamk_f32 v44, v167, 0x42600000, v210
	v_fmamk_f32 v45, v167, 0x42640000, v210
	v_fmamk_f32 v46, v167, 0x42680000, v210
	v_fmamk_f32 v47, v167, 0x426c0000, v210
	s_waitcnt vmcnt(7) lgkmcnt(6)
	v_mfma_f32_32x32x16_bf16 v[48:63], v[202:205], v[64:67], v[48:63]
	v_mfma_f32_32x32x16_bf16 v[32:47], v[206:209], v[64:67], v[32:47]
	s_waitcnt vmcnt(6) lgkmcnt(4)
	v_mfma_f32_32x32x16_bf16 v[32:47], v[114:117], v[68:71], v[32:47]
	v_mfma_f32_32x32x16_bf16 v[48:63], v[110:113], v[68:71], v[48:63]
	s_waitcnt vmcnt(5) lgkmcnt(0)
	v_mfma_f32_32x32x16_bf16 v[32:47], v[122:125], v[72:75], v[32:47]
	v_mfma_f32_32x32x16_bf16 v[48:63], v[118:121], v[72:75], v[48:63]
	s_waitcnt vmcnt(4)
	v_mfma_f32_32x32x16_bf16 v[32:47], v[130:133], v[76:79], v[32:47]
	v_mfma_f32_32x32x16_bf16 v[48:63], v[126:129], v[76:79], v[48:63]
	ds_read_b64_tr_b16 v[214:215], v134 offset:32768
	ds_read_b64_tr_b16 v[216:217], v134 offset:33280
	ds_read_b64_tr_b16 v[218:219], v134 offset:33792
	ds_read_b64_tr_b16 v[220:221], v134 offset:34304
	ds_read_b64_tr_b16 v[222:223], v134 offset:34816
	ds_read_b64_tr_b16 v[224:225], v134 offset:35328
	ds_read_b64_tr_b16 v[226:227], v134 offset:35840
	ds_read_b64_tr_b16 v[228:229], v134 offset:36352
	ds_read_b64_tr_b16 v[230:231], v134 offset:36864
	ds_read_b64_tr_b16 v[232:233], v134 offset:37376
	ds_read_b64_tr_b16 v[234:235], v134 offset:37888
	ds_read_b64_tr_b16 v[236:237], v134 offset:38400
	ds_read_b64_tr_b16 v[238:239], v134 offset:38912
	ds_read_b64_tr_b16 v[240:241], v134 offset:39424
	ds_read_b64_tr_b16 v[242:243], v134 offset:39936
	ds_read_b64_tr_b16 v[244:245], v134 offset:40448
	v_exp_f32_e32 v32, v32
	v_exp_f32_e32 v110, v52
	v_exp_f32_e32 v112, v36
	v_exp_f32_e32 v111, v53
	v_exp_f32_e32 v113, v37
	v_exp_f32_e32 v114, v54
	v_exp_f32_e32 v116, v38
	v_exp_f32_e32 v115, v55
	v_exp_f32_e32 v117, v39
	v_exp_f32_e32 v118, v56
	v_exp_f32_e32 v120, v40
	v_exp_f32_e32 v119, v57
	v_exp_f32_e32 v121, v41
	v_exp_f32_e32 v122, v58
	v_exp_f32_e32 v124, v42
	v_exp_f32_e32 v123, v59
	v_exp_f32_e32 v125, v43
	v_exp_f32_e32 v126, v60
	v_exp_f32_e32 v128, v44
	v_exp_f32_e32 v127, v61
	v_exp_f32_e32 v129, v45
	v_exp_f32_e32 v48, v48
	v_exp_f32_e32 v49, v49
	v_exp_f32_e32 v50, v50
	v_exp_f32_e32 v51, v51
	v_exp_f32_e32 v130, v62
	v_exp_f32_e32 v132, v46
	v_exp_f32_e32 v131, v63
	v_cvt_pk_bf16_f32 v36, v48, v49
	v_cvt_pk_bf16_f32 v37, v50, v51
	v_cvt_pk_bf16_f32 v38, v110, v111
	v_cvt_pk_bf16_f32 v39, v114, v115
	s_waitcnt lgkmcnt(0)
	s_nop 0
	v_mfma_f32_32x32x16_bf16 v[16:31], v[36:39], v[214:217], v[16:31]
	v_cvt_pk_bf16_f32 v52, v118, v119
	v_cvt_pk_bf16_f32 v53, v122, v123
	v_cvt_pk_bf16_f32 v54, v126, v127
	v_cvt_pk_bf16_f32 v55, v130, v131
	v_exp_f32_e32 v33, v33
	v_exp_f32_e32 v34, v34
	v_exp_f32_e32 v35, v35
	s_waitcnt lgkmcnt(0)
	v_mfma_f32_32x32x16_bf16 v[16:31], v[52:55], v[218:221], v[16:31]
	v_exp_f32_e32 v133, v47
	v_cvt_pk_bf16_f32 v40, v32, v33
	v_cvt_pk_bf16_f32 v41, v34, v35
	v_cvt_pk_bf16_f32 v42, v112, v113
	v_cvt_pk_bf16_f32 v43, v116, v117
	s_waitcnt lgkmcnt(0)
	s_nop 0
	v_mfma_f32_32x32x16_bf16 v[16:31], v[40:43], v[222:225], v[16:31]
	v_cvt_pk_bf16_f32 v56, v120, v121
	v_cvt_pk_bf16_f32 v57, v124, v125
	v_cvt_pk_bf16_f32 v58, v128, v129
	v_cvt_pk_bf16_f32 v59, v132, v133
	s_waitcnt lgkmcnt(0)
	s_nop 0
	v_mfma_f32_32x32x16_bf16 v[16:31], v[56:59], v[226:229], v[16:31]
	s_waitcnt lgkmcnt(2)
	v_mfma_f32_32x32x16_bf16 v[0:15], v[36:39], v[230:233], v[0:15]
	v_add_f32_e64 v36, v48, 0
	v_add_f32_e64 v37, v49, 0
	v_add_f32_e64 v32, v32, v36
	v_add_f32_e64 v33, v33, v37
	v_add_f32_e64 v32, v50, v32
	v_add_f32_e64 v33, v51, v33
	v_pk_add_f32 v[32:33], v[34:35], v[32:33]
	s_waitcnt lgkmcnt(0)
	v_mfma_f32_32x32x16_bf16 v[0:15], v[52:55], v[234:237], v[0:15]
	v_add_f32_e64 v32, v110, v32
	v_add_f32_e64 v33, v111, v33
	v_add_f32_e64 v32, v112, v32
	v_add_f32_e64 v33, v113, v33
	v_add_f32_e64 v32, v114, v32
	v_add_f32_e64 v33, v115, v33
	v_pk_add_f32 v[36:37], v[116:117], v[32:33]
	s_waitcnt lgkmcnt(0)
	v_mfma_f32_32x32x16_bf16 v[0:15], v[40:43], v[238:241], v[0:15]
	v_add_f32_e64 v36, v118, v36
	v_add_f32_e64 v37, v119, v37
	v_add_f32_e64 v44, v120, v36
	v_add_f32_e64 v45, v121, v37
	v_pk_add_f32 v[32:33], v[122:123], v[44:45]
	s_nop 0
	v_pk_add_f32 v[32:33], v[124:125], v[32:33]
	s_waitcnt lgkmcnt(0)
	v_mfma_f32_32x32x16_bf16 v[0:15], v[56:59], v[242:245], v[0:15]
	v_add_f32_e64 v32, v126, v32
	v_add_f32_e64 v33, v127, v33
	v_add_f32_e64 v32, v128, v32
	v_add_f32_e64 v33, v129, v33
	v_add_f32_e64 v32, v130, v32
	v_add_f32_e64 v33, v131, v33
	v_pk_add_f32 v[32:33], v[132:133], v[32:33]
	s_nop 0
	v_add_f32_e32 v32, v32, v33
	v_add_f32_e32 v109, v109, v32
	s_branch .LBB0_1359

; template <int TYPE> __device__ __forceinline__ void attn_unit(const AttnCtx& C, int b, int h, int qb, LAS unsigned char* lds, int tid_in, unsigned* counter) {
;     ...
;             if (active) {
;                 f32x16 p0, p1;
;                 const LAS unsigned char* kp = Kb + bo + hi * 1024 + r32 * 16;
; #pragma unroll
;                 for (int d0 = 0; d0 < 4; ++d0) {
;                     const bf16x8 a0 = *(const LAS bf16x8*)(kp + d0 * 2048), a1 = *(const LAS bf16x8*)(kp + d0 * 2048 + 512);
;                     if (d0 == 0) { p0 = MFMA32(a0, qr[0], (TYPE == 1 ? cvec : zvec)); p1 = MFMA32(a1, qr[0], (TYPE == 1 ? cvec : zvec)); }
;                     else { p0 = MFMA32(a0, qr[d0], p0); p1 = MFMA32(a1, qr[d0], p1); }
;                 }
;                 const int xi = sq - 64 * t - 4 * hi;
;                 if (TYPE == 0) {
;                     const float xf = (float)xi;
; #pragma unroll
;                     for (int r = 0; r < 16; ++r) { const float c = (float)((r & 3) + 8 * (r >> 2));
;                         p0[r] = fast_exp2(p0[r] - sl2 * fabsf(xf - c)); p1[r] = fast_exp2(p1[r] - sl2 * fabsf(xf - (c + 32.f))); }
;                 } else if (TYPE == 1) {
;                     const LAS float* fp = Fb + (t & 3) * 64 + 4 * hi;
; #pragma unroll
;                     for (int g = 0; g < 4; ++g) { const f32x4 fa = *(const LAS f32x4*)(fp + 8 * g), fb2 = *(const LAS f32x4*)(fp + 32 + 8 * g);
; #pragma unroll
;                         for (int i = 0; i < 4; i += 2) {
;                             const f32x2_t d0_ = (f32x2_t){p0[4 * g + i], p0[4 * g + i + 1]} - (f32x2_t){fa[i], fa[i + 1]}, d1_ = (f32x2_t){p1[4 * g + i], p1[4 * g + i + 1]} - (f32x2_t){fb2[i], fb2[i + 1]};
;                             p0[4 * g + i] = fast_exp2(d0_[0]); p0[4 * g + i + 1] = fast_exp2(d0_[1]); p1[4 * g + i] = fast_exp2(d1_[0]); p1[4 * g + i + 1] = fast_exp2(d1_[1]); } }
;                     if (t == cq) { const int qrel = 32 * (w & 1) + r32;
; #pragma unroll
;                         for (int r = 0; r < 16; ++r) { const int kv = crow(r, hi); if (kv > qrel) p0[r] = 0.f; if (kv + 32 > qrel) p1[r] = 0.f; } }
;                 } else {
;                     if (cq - t >= 3) { const float bc = relb[256];
; #pragma unroll
;                         for (int r = 0; r < 16; ++r) { p0[r] = fast_exp2(p0[r] + bc); p1[r] = fast_exp2(p1[r] + bc); }
;                     } else {
.LBB0_1380:
	s_cmp_gt_i32 s13, s12
	s_cbranch_scc1 .LBB0_1371
	s_sub_i32 s0, s15, 63
	s_waitcnt vmcnt(15)
	v_cvt_f32_i32_e32 v64, s0
	v_cmp_ngt_f32_e32 vcc, v168, v64
	s_cbranch_vccnz .LBB0_1371
	s_cmp_eq_u32 s13, s12
	s_cbranch_scc1 .Lt0diag_1
	v_add_u32_e32 v184, s17, v171
	v_add_u32_e32 v213, s15, v172
	v_cvt_f32_i32_e32 v213, v213
	v_mul_f32_e64 v210, -v167, v213
	ds_read_b128 v[202:205], v184
	ds_read_b128 v[206:209], v184 offset:512
	ds_read_b128 v[176:179], v184 offset:2048
	ds_read_b128 v[180:183], v184 offset:2560
	ds_read_b128 v[188:191], v184 offset:4608
	ds_read_b128 v[192:195], v184 offset:6144
	ds_read_b128 v[196:199], v184 offset:6656
	ds_read_b128 v[184:187], v184 offset:4096
	s_waitcnt vmcnt(14)
	v_add_u32_e32 v200, s17, v170
	v_mov_b32_e32 v80, v210
	v_fmamk_f32 v81, v167, 0x3f800000, v210
	v_fmamk_f32 v82, v167, 0x40000000, v210
	v_fmamk_f32 v83, v167, 0x40400000, v210
	v_fmamk_f32 v84, v167, 0x41000000, v210
	v_fmamk_f32 v85, v167, 0x41100000, v210
	v_fmamk_f32 v86, v167, 0x41200000, v210
	v_fmamk_f32 v87, v167, 0x41300000, v210
	v_fmamk_f32 v88, v167, 0x41800000, v210
	v_fmamk_f32 v89, v167, 0x41880000, v210
	v_fmamk_f32 v90, v167, 0x41900000, v210
	v_fmamk_f32 v91, v167, 0x41980000, v210
	v_fmamk_f32 v92, v167, 0x41c00000, v210
	v_fmamk_f32 v93, v167, 0x41c80000, v210
	v_fmamk_f32 v94, v167, 0x41d00000, v210
	v_fmamk_f32 v95, v167, 0x41d80000, v210
	v_fmamk_f32 v64, v167, 0x42000000, v210
	v_fmamk_f32 v65, v167, 0x42040000, v210
	v_fmamk_f32 v66, v167, 0x42080000, v210
	v_fmamk_f32 v67, v167, 0x420c0000, v210
	v_fmamk_f32 v68, v167, 0x42200000, v210
	v_fmamk_f32 v69, v167, 0x42240000, v210
	v_fmamk_f32 v70, v167, 0x42280000, v210
	v_fmamk_f32 v71, v167, 0x422c0000, v210
	v_fmamk_f32 v72, v167, 0x42400000, v210
	v_fmamk_f32 v73, v167, 0x42440000, v210
	v_fmamk_f32 v74, v167, 0x42480000, v210
	v_fmamk_f32 v75, v167, 0x424c0000, v210
	v_fmamk_f32 v76, v167, 0x42600000, v210
	v_fmamk_f32 v77, v167, 0x42640000, v210
	v_fmamk_f32 v78, v167, 0x42680000, v210
	v_fmamk_f32 v79, v167, 0x426c0000, v210
	s_waitcnt vmcnt(7) lgkmcnt(6)
	v_mfma_f32_32x32x16_bf16 v[80:95], v[202:205], v[112:115], v[80:95]
	v_mfma_f32_32x32x16_bf16 v[64:79], v[206:209], v[112:115], v[64:79]
	s_waitcnt vmcnt(6) lgkmcnt(4)
	v_mfma_f32_32x32x16_bf16 v[64:79], v[180:183], v[116:119], v[64:79]
	v_mfma_f32_32x32x16_bf16 v[80:95], v[176:179], v[116:119], v[80:95]
	s_waitcnt vmcnt(5) lgkmcnt(0)
	v_mfma_f32_32x32x16_bf16 v[64:79], v[188:191], v[120:123], v[64:79]
	v_mfma_f32_32x32x16_bf16 v[80:95], v[184:187], v[120:123], v[80:95]
	s_waitcnt vmcnt(4)
	v_mfma_f32_32x32x16_bf16 v[64:79], v[196:199], v[124:127], v[64:79]
	v_mfma_f32_32x32x16_bf16 v[80:95], v[192:195], v[124:127], v[80:95]
	ds_read_b64_tr_b16 v[214:215], v200 offset:32768
	ds_read_b64_tr_b16 v[216:217], v200 offset:33280
	ds_read_b64_tr_b16 v[218:219], v200 offset:33792
	ds_read_b64_tr_b16 v[220:221], v200 offset:34304
	ds_read_b64_tr_b16 v[222:223], v200 offset:34816
	ds_read_b64_tr_b16 v[224:225], v200 offset:35328
	ds_read_b64_tr_b16 v[226:227], v200 offset:35840
	ds_read_b64_tr_b16 v[228:229], v200 offset:36352
	ds_read_b64_tr_b16 v[230:231], v200 offset:36864
	ds_read_b64_tr_b16 v[232:233], v200 offset:37376
	ds_read_b64_tr_b16 v[234:235], v200 offset:37888
	ds_read_b64_tr_b16 v[236:237], v200 offset:38400
	ds_read_b64_tr_b16 v[238:239], v200 offset:38912
	ds_read_b64_tr_b16 v[240:241], v200 offset:39424
	ds_read_b64_tr_b16 v[242:243], v200 offset:39936
	ds_read_b64_tr_b16 v[244:245], v200 offset:40448
	v_exp_f32_e32 v64, v64
	v_exp_f32_e32 v176, v84
	v_exp_f32_e32 v178, v68
	v_exp_f32_e32 v177, v85
	v_exp_f32_e32 v179, v69
	v_exp_f32_e32 v180, v86
	v_exp_f32_e32 v182, v70
	v_exp_f32_e32 v181, v87
	v_exp_f32_e32 v183, v71
	v_exp_f32_e32 v184, v88
	v_exp_f32_e32 v186, v72
	v_exp_f32_e32 v185, v89
	v_exp_f32_e32 v187, v73
	v_exp_f32_e32 v188, v90
	v_exp_f32_e32 v190, v74
	v_exp_f32_e32 v189, v91
	v_exp_f32_e32 v191, v75
	v_exp_f32_e32 v192, v92
	v_exp_f32_e32 v194, v76
	v_exp_f32_e32 v193, v93
	v_exp_f32_e32 v195, v77
	v_exp_f32_e32 v80, v80
	v_exp_f32_e32 v81, v81
	v_exp_f32_e32 v82, v82
	v_exp_f32_e32 v83, v83
	v_exp_f32_e32 v196, v94
	v_exp_f32_e32 v198, v78
	v_exp_f32_e32 v197, v95
	v_cvt_pk_bf16_f32 v68, v80, v81
	v_cvt_pk_bf16_f32 v69, v82, v83
	v_cvt_pk_bf16_f32 v70, v176, v177
	v_cvt_pk_bf16_f32 v71, v180, v181
	s_waitcnt lgkmcnt(0)
	s_nop 0
	v_mfma_f32_32x32x16_bf16 v[48:63], v[68:71], v[214:217], v[48:63]
	v_cvt_pk_bf16_f32 v84, v184, v185
	v_cvt_pk_bf16_f32 v85, v188, v189
	v_cvt_pk_bf16_f32 v86, v192, v193
	v_cvt_pk_bf16_f32 v87, v196, v197
	v_exp_f32_e32 v65, v65
	v_exp_f32_e32 v66, v66
	v_exp_f32_e32 v67, v67
	s_waitcnt lgkmcnt(0)
	v_mfma_f32_32x32x16_bf16 v[48:63], v[84:87], v[218:221], v[48:63]
	v_exp_f32_e32 v199, v79
	v_cvt_pk_bf16_f32 v72, v64, v65
	v_cvt_pk_bf16_f32 v73, v66, v67
	v_cvt_pk_bf16_f32 v74, v178, v179
	v_cvt_pk_bf16_f32 v75, v182, v183
	s_waitcnt lgkmcnt(0)
	s_nop 0
	v_mfma_f32_32x32x16_bf16 v[48:63], v[72:75], v[222:225], v[48:63]
	v_cvt_pk_bf16_f32 v88, v186, v187
	v_cvt_pk_bf16_f32 v89, v190, v191
	v_cvt_pk_bf16_f32 v90, v194, v195
	v_cvt_pk_bf16_f32 v91, v198, v199
	s_waitcnt lgkmcnt(0)
	s_nop 0
	v_mfma_f32_32x32x16_bf16 v[48:63], v[88:91], v[226:229], v[48:63]
	s_waitcnt lgkmcnt(2)
	v_mfma_f32_32x32x16_bf16 v[32:47], v[68:71], v[230:233], v[32:47]
	v_add_f32_e64 v68, v80, 0
	v_add_f32_e64 v69, v81, 0
	v_add_f32_e64 v64, v64, v68
	v_add_f32_e64 v65, v65, v69
	v_add_f32_e64 v64, v82, v64
	v_add_f32_e64 v65, v83, v65
	v_pk_add_f32 v[64:65], v[66:67], v[64:65]
	s_waitcnt lgkmcnt(0)
	v_mfma_f32_32x32x16_bf16 v[32:47], v[84:87], v[234:237], v[32:47]
	v_add_f32_e64 v64, v176, v64
	v_add_f32_e64 v65, v177, v65
	v_add_f32_e64 v64, v178, v64
	v_add_f32_e64 v65, v179, v65
	v_add_f32_e64 v64, v180, v64
	v_add_f32_e64 v65, v181, v65
	v_pk_add_f32 v[68:69], v[182:183], v[64:65]
	s_waitcnt lgkmcnt(0)
	v_mfma_f32_32x32x16_bf16 v[32:47], v[72:75], v[238:241], v[32:47]
	v_add_f32_e64 v68, v184, v68
	v_add_f32_e64 v69, v185, v69
	v_add_f32_e64 v76, v186, v68
	v_add_f32_e64 v77, v187, v69
	v_pk_add_f32 v[64:65], v[188:189], v[76:77]
	s_nop 0
	v_pk_add_f32 v[64:65], v[190:191], v[64:65]
	s_waitcnt lgkmcnt(0)
	v_mfma_f32_32x32x16_bf16 v[32:47], v[88:91], v[242:245], v[32:47]
	v_add_f32_e64 v64, v192, v64
	v_add_f32_e64 v65, v193, v65
	v_add_f32_e64 v64, v194, v64
	v_add_f32_e64 v65, v195, v65
	v_add_f32_e64 v64, v196, v64
	v_add_f32_e64 v65, v197, v65
	v_pk_add_f32 v[64:65], v[198:199], v[64:65]
	s_nop 0
	v_add_f32_e32 v64, v64, v65
	v_add_f32_e32 v175, v175, v64
	s_branch .LBB0_1371
